# gemm2/gemm4 residual epilogue: two rounds of X loads in flight (v224-255), counted waits; on top of cvshift+g3waits
# baseline (speedup 1.0000x reference)
;     __device__ __forceinline__ void operator()(const f32x4 (&acc)[2][2][4][2], const Unit& u, int wr, int wc, int fr, int fq) const {
;     ...
;         const int b = u.pm / 9, r = (u.pm - 9 * b == 0) ? 4 : b;
;         const float* gate = modl + (size_t)r * 12288 + goff;
;         f32x4 gv[2][2];
; #pragma unroll
;         for (int bj = 0; bj < 2; ++bj)
; #pragma unroll
;             for (int n = 0; n < 2; ++n) gv[bj][n] = *(const f32x4*)(gate + col0 + bj * HALF + n * 16);
; #pragma unroll
;         for (int ai = 0; ai < 2; ++ai)
; #pragma unroll
;             for (int mp = 0; mp < 2; ++mp) { float* rowp = X + (size_t)(row0 + ai * HALF + mp * 32) * 2048 + col0;
;                 f32x4 xv[2][2][2];
; #pragma unroll
;                 for (int mm = 0; mm < 2; ++mm)
; #pragma unroll
;                     for (int bj = 0; bj < 2; ++bj)
; #pragma unroll
;                         for (int n = 0; n < 2; ++n) xv[mm][bj][n] = *(const f32x4*)(rowp + (size_t)mm * 16 * 2048 + bj * HALF + n * 16);
;                 __builtin_amdgcn_sched_barrier(0);
; #pragma unroll
;                 for (int mm = 0; mm < 2; ++mm)
; #pragma unroll
;                     for (int bj = 0; bj < 2; ++bj)
; #pragma unroll
;                         for (int n = 0; n < 2; ++n) *(f32x4*)(rowp + (size_t)mm * 16 * 2048 + bj * HALF + n * 16) = xv[mm][bj][n] + gv[bj][n] * acc[ai][bj][2 * mp + mm][n];
;                 __builtin_amdgcn_sched_barrier(0); }
.LBB0_838:
	s_mul_hi_i32 s12, s14, 0x38e38e39
	s_lshr_b32 s13, s12, 31
	s_ashr_i32 s12, s12, 1
	s_add_i32 s12, s12, s13
	s_mul_i32 s13, s12, -9
	s_sub_i32 s14, 0, s14
	s_cmp_lg_u32 s13, s14
	s_cselect_b32 s12, s12, 4
	s_mul_hi_i32 s13, s12, 0xc000
	s_mul_i32 s12, s12, 0xc000
	v_readlane_b32 s52, v220, 23
	v_readlane_b32 s53, v220, 24
	s_add_u32 s12, s52, s12
	s_addc_u32 s13, s53, s13
	v_lshlrev_b64 v[152:153], 2, v[128:129]
	v_lshl_add_u64 v[128:129], s[12:13], 0, v[152:153]
	s_mov_b64 s[12:13], 0x4000
	v_lshl_add_u64 v[130:131], v[128:129], 0, s[12:13]
	s_movk_i32 s12, 0x4000
	v_lshlrev_b64 v[144:145], 13, v[144:145]
	v_add_co_u32_e32 v128, vcc, s12, v128
	v_lshl_add_u64 v[144:145], s[8:9], 0, v[144:145]
	s_nop 0
	v_addc_co_u32_e32 v129, vcc, 0, v129, vcc
	v_lshl_add_u64 v[144:145], v[144:145], 0, v[152:153]
	s_mov_b32 s12, 0x20000
	v_add_co_u32_e32 v200, vcc, s12, v144
	global_load_dwordx4 v[136:139], v[130:131], off offset:64
	global_load_dwordx4 v[132:135], v[130:131], off offset:512
	global_load_dwordx4 v[140:143], v[128:129], off
	s_nop 0
	global_load_dwordx4 v[128:131], v[130:131], off offset:576
	v_addc_co_u32_e32 v201, vcc, 0, v145, vcc
	global_load_dwordx4 v[152:155], v[144:145], off
	global_load_dwordx4 v[156:159], v[144:145], off offset:64
	global_load_dwordx4 v[162:165], v[144:145], off offset:512
	global_load_dwordx4 v[166:169], v[144:145], off offset:576
	global_load_dwordx4 v[170:173], v[200:201], off
	global_load_dwordx4 v[174:177], v[200:201], off offset:64
	global_load_dwordx4 v[178:181], v[200:201], off offset:512
	global_load_dwordx4 v[196:199], v[200:201], off offset:576
	v_add_co_u32_e32 v204, vcc, s90, v144
	s_mov_b32 s12, 0x60000
	s_nop 0
	v_addc_co_u32_e32 v205, vcc, 0, v145, vcc
	v_add_co_u32_e32 v206, vcc, s12, v144
	v_lshl_add_u64 v[202:203], v[144:145], 0, s[88:89]
	s_nop 0
	v_addc_co_u32_e32 v207, vcc, 0, v145, vcc
	global_load_dwordx4 v[224:227], v[202:203], off offset:64
	global_load_dwordx4 v[228:231], v[202:203], off offset:512
	global_load_dwordx4 v[232:235], v[204:205], off
	global_load_dwordx4 v[236:239], v[202:203], off offset:576
	global_load_dwordx4 v[240:243], v[206:207], off
	global_load_dwordx4 v[244:247], v[206:207], off offset:64
	global_load_dwordx4 v[248:251], v[206:207], off offset:512
	global_load_dwordx4 v[252:255], v[206:207], off offset:576
	s_waitcnt vmcnt(8)
	v_pk_fma_f32 v[106:107], v[106:107], v[130:131], v[168:169]
	v_pk_fma_f32 v[104:105], v[104:105], v[128:129], v[166:167]
	global_store_dwordx4 v[144:145], v[104:107], off offset:576
	v_pk_fma_f32 v[126:127], v[126:127], v[142:143], v[154:155]
	v_pk_fma_f32 v[124:125], v[124:125], v[140:141], v[152:153]
	v_pk_fma_f32 v[106:107], v[118:119], v[142:143], v[172:173]
	v_pk_fma_f32 v[104:105], v[116:117], v[140:141], v[170:171]
	v_pk_fma_f32 v[122:123], v[122:123], v[138:139], v[158:159]
	v_pk_fma_f32 v[120:121], v[120:121], v[136:137], v[156:157]
	v_pk_fma_f32 v[114:115], v[114:115], v[134:135], v[164:165]
	v_pk_fma_f32 v[112:113], v[112:113], v[132:133], v[162:163]
	global_store_dwordx4 v[200:201], v[104:107], off
	v_pk_fma_f32 v[102:103], v[102:103], v[134:135], v[180:181]
	v_pk_fma_f32 v[100:101], v[100:101], v[132:133], v[178:179]
	v_pk_fma_f32 v[106:107], v[110:111], v[138:139], v[176:177]
	v_pk_fma_f32 v[104:105], v[108:109], v[136:137], v[174:175]
	v_pk_fma_f32 v[98:99], v[98:99], v[130:131], v[198:199]
	v_pk_fma_f32 v[96:97], v[96:97], v[128:129], v[196:197]
	global_store_dwordx4 v[144:145], v[124:127], off
	global_store_dwordx4 v[144:145], v[120:123], off offset:64
	global_store_dwordx4 v[144:145], v[112:115], off offset:512
	global_store_dwordx4 v[200:201], v[104:107], off offset:64
	global_store_dwordx4 v[200:201], v[100:103], off offset:512
	global_store_dwordx4 v[200:201], v[96:99], off offset:576
	s_nop 1
	s_mov_b64 s[12:13], 0x100000
	v_add_co_u32_e32 v98, vcc, s73, v144
	v_lshl_add_u64 v[96:97], v[144:145], 0, s[12:13]
	s_nop 0
	v_addc_co_u32_e32 v99, vcc, 0, v145, vcc
	s_mov_b32 s12, 0x120000
	v_add_co_u32_e32 v100, vcc, s12, v144
	global_load_dwordx4 v[152:155], v[96:97], off offset:64
	global_load_dwordx4 v[156:159], v[96:97], off offset:512
	global_load_dwordx4 v[162:165], v[98:99], off
	global_load_dwordx4 v[166:169], v[96:97], off offset:576
	v_addc_co_u32_e32 v101, vcc, 0, v145, vcc
	global_load_dwordx4 v[170:173], v[100:101], off
	global_load_dwordx4 v[174:177], v[100:101], off offset:64
	global_load_dwordx4 v[178:181], v[100:101], off offset:512
	global_load_dwordx4 v[196:199], v[100:101], off offset:576
	s_waitcnt vmcnt(16)
;     __device__ __forceinline__ void operator()(const f32x4 (&acc)[2][2][4][2], const Unit& u, int wr, int wc, int fr, int fq) const {
;     ...
;         for (int ai = 0; ai < 2; ++ai)
; #pragma unroll
;             for (int mp = 0; mp < 2; ++mp) { float* rowp = X + (size_t)(row0 + ai * HALF + mp * 32) * 2048 + col0;
;                 f32x4 xv[2][2][2];
; #pragma unroll
;                 for (int mm = 0; mm < 2; ++mm)
; #pragma unroll
;                     for (int bj = 0; bj < 2; ++bj)
; #pragma unroll
;                         for (int n = 0; n < 2; ++n) xv[mm][bj][n] = *(const f32x4*)(rowp + (size_t)mm * 16 * 2048 + bj * HALF + n * 16);
;                 __builtin_amdgcn_sched_barrier(0);
; #pragma unroll
;                 for (int mm = 0; mm < 2; ++mm)
; #pragma unroll
;                     for (int bj = 0; bj < 2; ++bj)
; #pragma unroll
;                         for (int n = 0; n < 2; ++n) *(f32x4*)(rowp + (size_t)mm * 16 * 2048 + bj * HALF + n * 16) = xv[mm][bj][n] + gv[bj][n] * acc[ai][bj][2 * mp + mm][n];
;                 __builtin_amdgcn_sched_barrier(0); }
	v_pk_fma_f32 v[74:75], v[74:75], v[130:131], v[238:239]
	v_pk_fma_f32 v[72:73], v[72:73], v[128:129], v[236:237]
	global_store_dwordx4 v[202:203], v[72:75], off offset:576
	v_pk_fma_f32 v[94:95], v[94:95], v[142:143], v[234:235]
	v_pk_fma_f32 v[92:93], v[92:93], v[140:141], v[232:233]
	v_pk_fma_f32 v[74:75], v[86:87], v[142:143], v[242:243]
	v_pk_fma_f32 v[72:73], v[84:85], v[140:141], v[240:241]
	v_pk_fma_f32 v[90:91], v[90:91], v[138:139], v[226:227]
	v_pk_fma_f32 v[88:89], v[88:89], v[136:137], v[224:225]
	v_pk_fma_f32 v[82:83], v[82:83], v[134:135], v[230:231]
	v_pk_fma_f32 v[80:81], v[80:81], v[132:133], v[228:229]
	global_store_dwordx4 v[206:207], v[72:75], off
	v_pk_fma_f32 v[70:71], v[70:71], v[134:135], v[250:251]
	v_pk_fma_f32 v[68:69], v[68:69], v[132:133], v[248:249]
	v_pk_fma_f32 v[74:75], v[78:79], v[138:139], v[246:247]
	v_pk_fma_f32 v[72:73], v[76:77], v[136:137], v[244:245]
	v_pk_fma_f32 v[66:67], v[66:67], v[130:131], v[254:255]
	v_pk_fma_f32 v[64:65], v[64:65], v[128:129], v[252:253]
	global_store_dwordx4 v[204:205], v[92:95], off
	global_store_dwordx4 v[202:203], v[88:91], off offset:64
	global_store_dwordx4 v[202:203], v[80:83], off offset:512
	global_store_dwordx4 v[206:207], v[72:75], off offset:64
	global_store_dwordx4 v[206:207], v[68:71], off offset:512
	global_store_dwordx4 v[206:207], v[64:67], off offset:576
	s_nop 1
	s_mov_b64 s[12:13], 0x140000
	v_lshl_add_u64 v[64:65], v[144:145], 0, s[12:13]
	s_mov_b32 s12, 0x140000
	v_add_co_u32_e32 v66, vcc, s12, v144
	s_mov_b32 s12, 0x160000
	s_nop 0
	v_addc_co_u32_e32 v67, vcc, 0, v145, vcc
	v_add_co_u32_e32 v68, vcc, s12, v144
	global_load_dwordx4 v[224:227], v[64:65], off offset:64
	global_load_dwordx4 v[228:231], v[64:65], off offset:512
	global_load_dwordx4 v[232:235], v[66:67], off
	global_load_dwordx4 v[236:239], v[64:65], off offset:576
	v_addc_co_u32_e32 v69, vcc, 0, v145, vcc
	global_load_dwordx4 v[240:243], v[68:69], off
	global_load_dwordx4 v[244:247], v[68:69], off offset:64
	global_load_dwordx4 v[248:251], v[68:69], off offset:512
	global_load_dwordx4 v[252:255], v[68:69], off offset:576
	s_waitcnt vmcnt(16)
	v_pk_fma_f32 v[42:43], v[42:43], v[130:131], v[168:169]
	v_pk_fma_f32 v[40:41], v[40:41], v[128:129], v[166:167]
	global_store_dwordx4 v[96:97], v[40:43], off offset:576
	v_pk_fma_f32 v[62:63], v[62:63], v[142:143], v[164:165]
	v_pk_fma_f32 v[60:61], v[60:61], v[140:141], v[162:163]
	v_pk_fma_f32 v[42:43], v[54:55], v[142:143], v[172:173]
	v_pk_fma_f32 v[40:41], v[52:53], v[140:141], v[170:171]
	v_pk_fma_f32 v[58:59], v[58:59], v[138:139], v[154:155]
	v_pk_fma_f32 v[56:57], v[56:57], v[136:137], v[152:153]
	v_pk_fma_f32 v[50:51], v[50:51], v[134:135], v[158:159]
	v_pk_fma_f32 v[48:49], v[48:49], v[132:133], v[156:157]
	global_store_dwordx4 v[100:101], v[40:43], off
	v_pk_fma_f32 v[38:39], v[38:39], v[134:135], v[180:181]
	v_pk_fma_f32 v[36:37], v[36:37], v[132:133], v[178:179]
	v_pk_fma_f32 v[42:43], v[46:47], v[138:139], v[176:177]
	v_pk_fma_f32 v[40:41], v[44:45], v[136:137], v[174:175]
	v_pk_fma_f32 v[34:35], v[34:35], v[130:131], v[198:199]
	v_pk_fma_f32 v[32:33], v[32:33], v[128:129], v[196:197]
	global_store_dwordx4 v[98:99], v[60:63], off
	global_store_dwordx4 v[96:97], v[56:59], off offset:64
	global_store_dwordx4 v[96:97], v[48:51], off offset:512
	global_store_dwordx4 v[100:101], v[40:43], off offset:64
	global_store_dwordx4 v[100:101], v[36:39], off offset:512
	global_store_dwordx4 v[100:101], v[32:35], off offset:576
	s_waitcnt vmcnt(8)
	v_pk_fma_f32 v[10:11], v[10:11], v[130:131], v[238:239]
	v_pk_fma_f32 v[8:9], v[8:9], v[128:129], v[236:237]
	global_store_dwordx4 v[64:65], v[8:11], off offset:576
	v_pk_fma_f32 v[30:31], v[30:31], v[142:143], v[234:235]
	v_pk_fma_f32 v[28:29], v[28:29], v[140:141], v[232:233]
	v_pk_fma_f32 v[10:11], v[22:23], v[142:143], v[242:243]
	v_pk_fma_f32 v[8:9], v[20:21], v[140:141], v[240:241]
	v_pk_fma_f32 v[26:27], v[26:27], v[138:139], v[226:227]
	v_pk_fma_f32 v[24:25], v[24:25], v[136:137], v[224:225]
	v_pk_fma_f32 v[18:19], v[18:19], v[134:135], v[230:231]
	v_pk_fma_f32 v[16:17], v[16:17], v[132:133], v[228:229]
	global_store_dwordx4 v[68:69], v[8:11], off
	v_pk_fma_f32 v[6:7], v[6:7], v[134:135], v[250:251]
	v_pk_fma_f32 v[4:5], v[4:5], v[132:133], v[248:249]
	v_pk_fma_f32 v[10:11], v[14:15], v[138:139], v[246:247]
	v_pk_fma_f32 v[8:9], v[12:13], v[136:137], v[244:245]
	v_pk_fma_f32 v[2:3], v[2:3], v[130:131], v[254:255]
	v_pk_fma_f32 v[0:1], v[0:1], v[128:129], v[252:253]
	global_store_dwordx4 v[66:67], v[28:31], off
	global_store_dwordx4 v[64:65], v[24:27], off offset:64
	global_store_dwordx4 v[64:65], v[16:19], off offset:512
	global_store_dwordx4 v[68:69], v[8:11], off offset:64
	global_store_dwordx4 v[68:69], v[4:7], off offset:512
	global_store_dwordx4 v[68:69], v[0:3], off offset:576
	s_and_b64 vcc, exec, s[2:3]
	s_mov_b64 s[2:3], -1
	s_cbranch_vccnz .LBB0_813

;     __device__ __forceinline__ void operator()(const f32x4 (&acc)[2][2][4][2], const Unit& u, int wr, int wc, int fr, int fq) const {
;     ...
;         const int b = u.pm / 9, r = (u.pm - 9 * b == 0) ? 4 : b;
;         const float* gate = modl + (size_t)r * 12288 + goff;
;         f32x4 gv[2][2];
; #pragma unroll
;         for (int bj = 0; bj < 2; ++bj)
; #pragma unroll
;             for (int n = 0; n < 2; ++n) gv[bj][n] = *(const f32x4*)(gate + col0 + bj * HALF + n * 16);
; #pragma unroll
;         for (int ai = 0; ai < 2; ++ai)
; #pragma unroll
;             for (int mp = 0; mp < 2; ++mp) { float* rowp = X + (size_t)(row0 + ai * HALF + mp * 32) * 2048 + col0;
;                 f32x4 xv[2][2][2];
; #pragma unroll
;                 for (int mm = 0; mm < 2; ++mm)
; #pragma unroll
;                     for (int bj = 0; bj < 2; ++bj)
; #pragma unroll
;                         for (int n = 0; n < 2; ++n) xv[mm][bj][n] = *(const f32x4*)(rowp + (size_t)mm * 16 * 2048 + bj * HALF + n * 16);
;                 __builtin_amdgcn_sched_barrier(0);
; #pragma unroll
;                 for (int mm = 0; mm < 2; ++mm)
; #pragma unroll
;                     for (int bj = 0; bj < 2; ++bj)
; #pragma unroll
;                         for (int n = 0; n < 2; ++n) *(f32x4*)(rowp + (size_t)mm * 16 * 2048 + bj * HALF + n * 16) = xv[mm][bj][n] + gv[bj][n] * acc[ai][bj][2 * mp + mm][n];
;                 __builtin_amdgcn_sched_barrier(0); }
.LBB0_1131:
	s_mul_hi_i32 s12, s14, 0x38e38e39
	s_lshr_b32 s13, s12, 31
	s_ashr_i32 s12, s12, 1
	s_add_i32 s12, s12, s13
	s_mul_i32 s13, s12, -9
	s_sub_i32 s14, 0, s14
	s_cmp_lg_u32 s13, s14
	s_cselect_b32 s12, s12, 4
	s_mul_hi_i32 s13, s12, 0xc000
	s_mul_i32 s12, s12, 0xc000
	v_readlane_b32 s52, v220, 23
	v_readlane_b32 s53, v220, 24
	s_add_u32 s12, s52, s12
	s_addc_u32 s13, s53, s13
	v_lshlrev_b64 v[152:153], 2, v[128:129]
	v_lshl_add_u64 v[128:129], s[12:13], 0, v[152:153]
	s_mov_b64 s[12:13], 0xa000
	v_lshl_add_u64 v[130:131], v[128:129], 0, s[12:13]
	s_mov_b32 s12, 0xa000
	v_lshlrev_b64 v[144:145], 13, v[144:145]
	v_add_co_u32_e32 v128, vcc, s12, v128
	v_lshl_add_u64 v[144:145], s[8:9], 0, v[144:145]
	s_nop 0
	v_addc_co_u32_e32 v129, vcc, 0, v129, vcc
	v_lshl_add_u64 v[144:145], v[144:145], 0, v[152:153]
	s_mov_b32 s12, 0x20000
	v_add_co_u32_e32 v200, vcc, s12, v144
	global_load_dwordx4 v[136:139], v[130:131], off offset:64
	global_load_dwordx4 v[132:135], v[130:131], off offset:512
	global_load_dwordx4 v[140:143], v[128:129], off
	s_nop 0
	global_load_dwordx4 v[128:131], v[130:131], off offset:576
	v_addc_co_u32_e32 v201, vcc, 0, v145, vcc
	global_load_dwordx4 v[152:155], v[144:145], off
	global_load_dwordx4 v[156:159], v[144:145], off offset:64
	global_load_dwordx4 v[162:165], v[144:145], off offset:512
	global_load_dwordx4 v[166:169], v[144:145], off offset:576
	global_load_dwordx4 v[170:173], v[200:201], off
	global_load_dwordx4 v[174:177], v[200:201], off offset:64
	global_load_dwordx4 v[178:181], v[200:201], off offset:512
	global_load_dwordx4 v[196:199], v[200:201], off offset:576
	v_add_co_u32_e32 v204, vcc, s90, v144
	s_mov_b32 s12, 0x60000
	s_nop 0
	v_addc_co_u32_e32 v205, vcc, 0, v145, vcc
	v_add_co_u32_e32 v206, vcc, s12, v144
	v_lshl_add_u64 v[202:203], v[144:145], 0, s[88:89]
	s_nop 0
	v_addc_co_u32_e32 v207, vcc, 0, v145, vcc
	global_load_dwordx4 v[224:227], v[202:203], off offset:64
	global_load_dwordx4 v[228:231], v[202:203], off offset:512
	global_load_dwordx4 v[232:235], v[204:205], off
	global_load_dwordx4 v[236:239], v[202:203], off offset:576
	global_load_dwordx4 v[240:243], v[206:207], off
	global_load_dwordx4 v[244:247], v[206:207], off offset:64
	global_load_dwordx4 v[248:251], v[206:207], off offset:512
	global_load_dwordx4 v[252:255], v[206:207], off offset:576
	s_waitcnt vmcnt(8)
	v_pk_fma_f32 v[106:107], v[106:107], v[130:131], v[168:169]
	v_pk_fma_f32 v[104:105], v[104:105], v[128:129], v[166:167]
	global_store_dwordx4 v[144:145], v[104:107], off offset:576
	v_pk_fma_f32 v[126:127], v[126:127], v[142:143], v[154:155]
	v_pk_fma_f32 v[124:125], v[124:125], v[140:141], v[152:153]
	v_pk_fma_f32 v[106:107], v[118:119], v[142:143], v[172:173]
	v_pk_fma_f32 v[104:105], v[116:117], v[140:141], v[170:171]
	v_pk_fma_f32 v[122:123], v[122:123], v[138:139], v[158:159]
	v_pk_fma_f32 v[120:121], v[120:121], v[136:137], v[156:157]
	v_pk_fma_f32 v[114:115], v[114:115], v[134:135], v[164:165]
	v_pk_fma_f32 v[112:113], v[112:113], v[132:133], v[162:163]
	global_store_dwordx4 v[200:201], v[104:107], off
	v_pk_fma_f32 v[102:103], v[102:103], v[134:135], v[180:181]
	v_pk_fma_f32 v[100:101], v[100:101], v[132:133], v[178:179]
	v_pk_fma_f32 v[106:107], v[110:111], v[138:139], v[176:177]
	v_pk_fma_f32 v[104:105], v[108:109], v[136:137], v[174:175]
	v_pk_fma_f32 v[98:99], v[98:99], v[130:131], v[198:199]
	v_pk_fma_f32 v[96:97], v[96:97], v[128:129], v[196:197]
	global_store_dwordx4 v[144:145], v[124:127], off
	global_store_dwordx4 v[144:145], v[120:123], off offset:64
	global_store_dwordx4 v[144:145], v[112:115], off offset:512
	global_store_dwordx4 v[200:201], v[104:107], off offset:64
	global_store_dwordx4 v[200:201], v[100:103], off offset:512
	global_store_dwordx4 v[200:201], v[96:99], off offset:576
	s_nop 1
	s_mov_b64 s[12:13], 0x100000
	v_add_co_u32_e32 v98, vcc, s73, v144
	v_lshl_add_u64 v[96:97], v[144:145], 0, s[12:13]
	s_nop 0
	v_addc_co_u32_e32 v99, vcc, 0, v145, vcc
	s_mov_b32 s12, 0x120000
	v_add_co_u32_e32 v100, vcc, s12, v144
	global_load_dwordx4 v[152:155], v[96:97], off offset:64
	global_load_dwordx4 v[156:159], v[96:97], off offset:512
	global_load_dwordx4 v[162:165], v[98:99], off
	global_load_dwordx4 v[166:169], v[96:97], off offset:576
	v_addc_co_u32_e32 v101, vcc, 0, v145, vcc
	global_load_dwordx4 v[170:173], v[100:101], off
	global_load_dwordx4 v[174:177], v[100:101], off offset:64
	global_load_dwordx4 v[178:181], v[100:101], off offset:512
	global_load_dwordx4 v[196:199], v[100:101], off offset:576
	s_waitcnt vmcnt(16)
;     __device__ __forceinline__ void operator()(const f32x4 (&acc)[2][2][4][2], const Unit& u, int wr, int wc, int fr, int fq) const {
;     ...
;         for (int ai = 0; ai < 2; ++ai)
; #pragma unroll
;             for (int mp = 0; mp < 2; ++mp) { float* rowp = X + (size_t)(row0 + ai * HALF + mp * 32) * 2048 + col0;
;                 f32x4 xv[2][2][2];
; #pragma unroll
;                 for (int mm = 0; mm < 2; ++mm)
; #pragma unroll
;                     for (int bj = 0; bj < 2; ++bj)
; #pragma unroll
;                         for (int n = 0; n < 2; ++n) xv[mm][bj][n] = *(const f32x4*)(rowp + (size_t)mm * 16 * 2048 + bj * HALF + n * 16);
;                 __builtin_amdgcn_sched_barrier(0);
; #pragma unroll
;                 for (int mm = 0; mm < 2; ++mm)
; #pragma unroll
;                     for (int bj = 0; bj < 2; ++bj)
; #pragma unroll
;                         for (int n = 0; n < 2; ++n) *(f32x4*)(rowp + (size_t)mm * 16 * 2048 + bj * HALF + n * 16) = xv[mm][bj][n] + gv[bj][n] * acc[ai][bj][2 * mp + mm][n];
;                 __builtin_amdgcn_sched_barrier(0); }
	v_pk_fma_f32 v[74:75], v[74:75], v[130:131], v[238:239]
	v_pk_fma_f32 v[72:73], v[72:73], v[128:129], v[236:237]
	global_store_dwordx4 v[202:203], v[72:75], off offset:576
	v_pk_fma_f32 v[94:95], v[94:95], v[142:143], v[234:235]
	v_pk_fma_f32 v[92:93], v[92:93], v[140:141], v[232:233]
	v_pk_fma_f32 v[74:75], v[86:87], v[142:143], v[242:243]
	v_pk_fma_f32 v[72:73], v[84:85], v[140:141], v[240:241]
	v_pk_fma_f32 v[90:91], v[90:91], v[138:139], v[226:227]
	v_pk_fma_f32 v[88:89], v[88:89], v[136:137], v[224:225]
	v_pk_fma_f32 v[82:83], v[82:83], v[134:135], v[230:231]
	v_pk_fma_f32 v[80:81], v[80:81], v[132:133], v[228:229]
	global_store_dwordx4 v[206:207], v[72:75], off
	v_pk_fma_f32 v[70:71], v[70:71], v[134:135], v[250:251]
	v_pk_fma_f32 v[68:69], v[68:69], v[132:133], v[248:249]
	v_pk_fma_f32 v[74:75], v[78:79], v[138:139], v[246:247]
	v_pk_fma_f32 v[72:73], v[76:77], v[136:137], v[244:245]
	v_pk_fma_f32 v[66:67], v[66:67], v[130:131], v[254:255]
	v_pk_fma_f32 v[64:65], v[64:65], v[128:129], v[252:253]
	global_store_dwordx4 v[204:205], v[92:95], off
	global_store_dwordx4 v[202:203], v[88:91], off offset:64
	global_store_dwordx4 v[202:203], v[80:83], off offset:512
	global_store_dwordx4 v[206:207], v[72:75], off offset:64
	global_store_dwordx4 v[206:207], v[68:71], off offset:512
	global_store_dwordx4 v[206:207], v[64:67], off offset:576
	s_nop 1
	s_mov_b64 s[12:13], 0x140000
	v_lshl_add_u64 v[64:65], v[144:145], 0, s[12:13]
	s_mov_b32 s12, 0x140000
	v_add_co_u32_e32 v66, vcc, s12, v144
	s_mov_b32 s12, 0x160000
	s_nop 0
	v_addc_co_u32_e32 v67, vcc, 0, v145, vcc
	v_add_co_u32_e32 v68, vcc, s12, v144
	global_load_dwordx4 v[224:227], v[64:65], off offset:64
	global_load_dwordx4 v[228:231], v[64:65], off offset:512
	global_load_dwordx4 v[232:235], v[66:67], off
	global_load_dwordx4 v[236:239], v[64:65], off offset:576
	v_addc_co_u32_e32 v69, vcc, 0, v145, vcc
	global_load_dwordx4 v[240:243], v[68:69], off
	global_load_dwordx4 v[244:247], v[68:69], off offset:64
	global_load_dwordx4 v[248:251], v[68:69], off offset:512
	global_load_dwordx4 v[252:255], v[68:69], off offset:576
	s_waitcnt vmcnt(16)
	v_pk_fma_f32 v[42:43], v[42:43], v[130:131], v[168:169]
	v_pk_fma_f32 v[40:41], v[40:41], v[128:129], v[166:167]
	global_store_dwordx4 v[96:97], v[40:43], off offset:576
	v_pk_fma_f32 v[62:63], v[62:63], v[142:143], v[164:165]
	v_pk_fma_f32 v[60:61], v[60:61], v[140:141], v[162:163]
	v_pk_fma_f32 v[42:43], v[54:55], v[142:143], v[172:173]
	v_pk_fma_f32 v[40:41], v[52:53], v[140:141], v[170:171]
	v_pk_fma_f32 v[58:59], v[58:59], v[138:139], v[154:155]
	v_pk_fma_f32 v[56:57], v[56:57], v[136:137], v[152:153]
	v_pk_fma_f32 v[50:51], v[50:51], v[134:135], v[158:159]
	v_pk_fma_f32 v[48:49], v[48:49], v[132:133], v[156:157]
	global_store_dwordx4 v[100:101], v[40:43], off
	v_pk_fma_f32 v[38:39], v[38:39], v[134:135], v[180:181]
	v_pk_fma_f32 v[36:37], v[36:37], v[132:133], v[178:179]
	v_pk_fma_f32 v[42:43], v[46:47], v[138:139], v[176:177]
	v_pk_fma_f32 v[40:41], v[44:45], v[136:137], v[174:175]
	v_pk_fma_f32 v[34:35], v[34:35], v[130:131], v[198:199]
	v_pk_fma_f32 v[32:33], v[32:33], v[128:129], v[196:197]
	global_store_dwordx4 v[98:99], v[60:63], off
	global_store_dwordx4 v[96:97], v[56:59], off offset:64
	global_store_dwordx4 v[96:97], v[48:51], off offset:512
	global_store_dwordx4 v[100:101], v[40:43], off offset:64
	global_store_dwordx4 v[100:101], v[36:39], off offset:512
	global_store_dwordx4 v[100:101], v[32:35], off offset:576
	s_waitcnt vmcnt(8)
	v_pk_fma_f32 v[10:11], v[10:11], v[130:131], v[238:239]
	v_pk_fma_f32 v[8:9], v[8:9], v[128:129], v[236:237]
	global_store_dwordx4 v[64:65], v[8:11], off offset:576
	v_pk_fma_f32 v[30:31], v[30:31], v[142:143], v[234:235]
	v_pk_fma_f32 v[28:29], v[28:29], v[140:141], v[232:233]
	v_pk_fma_f32 v[10:11], v[22:23], v[142:143], v[242:243]
	v_pk_fma_f32 v[8:9], v[20:21], v[140:141], v[240:241]
	v_pk_fma_f32 v[26:27], v[26:27], v[138:139], v[226:227]
	v_pk_fma_f32 v[24:25], v[24:25], v[136:137], v[224:225]
	v_pk_fma_f32 v[18:19], v[18:19], v[134:135], v[230:231]
	v_pk_fma_f32 v[16:17], v[16:17], v[132:133], v[228:229]
	global_store_dwordx4 v[68:69], v[8:11], off
	v_pk_fma_f32 v[6:7], v[6:7], v[134:135], v[250:251]
	v_pk_fma_f32 v[4:5], v[4:5], v[132:133], v[248:249]
	v_pk_fma_f32 v[10:11], v[14:15], v[138:139], v[246:247]
	v_pk_fma_f32 v[8:9], v[12:13], v[136:137], v[244:245]
	v_pk_fma_f32 v[2:3], v[2:3], v[130:131], v[254:255]
	v_pk_fma_f32 v[0:1], v[0:1], v[128:129], v[252:253]
	global_store_dwordx4 v[66:67], v[28:31], off
	global_store_dwordx4 v[64:65], v[24:27], off offset:64
	global_store_dwordx4 v[64:65], v[16:19], off offset:512
	global_store_dwordx4 v[68:69], v[8:11], off offset:64
	global_store_dwordx4 v[68:69], v[4:7], off offset:512
	global_store_dwordx4 v[68:69], v[0:3], off offset:576
	s_and_b64 vcc, exec, s[2:3]
	s_mov_b64 s[2:3], -1
	s_cbranch_vccnz .LBB0_1106

; __global__ void __launch_bounds__(NTHREADS, 2) fwd(Args args) {
	.amdhsa_kernel _Z3fwd4Args
		.amdhsa_group_segment_fixed_size 0
		.amdhsa_private_segment_fixed_size 0
		.amdhsa_kernarg_size 432
		.amdhsa_user_sgpr_count 2
		.amdhsa_user_sgpr_dispatch_ptr 0
		.amdhsa_user_sgpr_queue_ptr 0
		.amdhsa_user_sgpr_kernarg_segment_ptr 1
		.amdhsa_user_sgpr_dispatch_id 0
		.amdhsa_user_sgpr_kernarg_preload_length 0
		.amdhsa_user_sgpr_kernarg_preload_offset 0
		.amdhsa_user_sgpr_private_segment_size 0
		.amdhsa_uses_dynamic_stack 0
		.amdhsa_enable_private_segment 0
		.amdhsa_system_sgpr_workgroup_id_x 1
		.amdhsa_system_sgpr_workgroup_id_y 0
		.amdhsa_system_sgpr_workgroup_id_z 0
		.amdhsa_system_sgpr_workgroup_info 0
		.amdhsa_system_vgpr_workitem_id 0
		.amdhsa_next_free_vgpr 256
		.amdhsa_next_free_sgpr 100
		.amdhsa_accum_offset 256
		.amdhsa_reserve_vcc 1
		.amdhsa_float_round_mode_32 0
		.amdhsa_float_round_mode_16_64 0
		.amdhsa_float_denorm_mode_32 3
		.amdhsa_float_denorm_mode_16_64 3
		.amdhsa_dx10_clamp 1
		.amdhsa_ieee_mode 1
		.amdhsa_fp16_overflow 0
		.amdhsa_tg_split 0
		.amdhsa_exception_fp_ieee_invalid_op 0
		.amdhsa_exception_fp_denorm_src 0
		.amdhsa_exception_fp_ieee_div_zero 0
		.amdhsa_exception_fp_ieee_overflow 0
		.amdhsa_exception_fp_ieee_underflow 0
		.amdhsa_exception_fp_ieee_inexact 0
		.amdhsa_exception_int_div_zero 0
	.end_amdhsa_kernel

; __global__ void __launch_bounds__(NTHREADS, 2) fwd(Args args) {
amdhsa.kernels:
  - .agpr_count:     0
    .args:
      - .offset:         0
        .size:           176
        .value_kind:     by_value
      - .offset:         176
        .size:           4
        .value_kind:     hidden_block_count_x
      - .offset:         180
        .size:           4
        .value_kind:     hidden_block_count_y
      - .offset:         184
        .size:           4
        .value_kind:     hidden_block_count_z
      - .offset:         188
        .size:           2
        .value_kind:     hidden_group_size_x
      - .offset:         190
        .size:           2
        .value_kind:     hidden_group_size_y
      - .offset:         192
        .size:           2
        .value_kind:     hidden_group_size_z
      - .offset:         194
        .size:           2
        .value_kind:     hidden_remainder_x
      - .offset:         196
        .size:           2
        .value_kind:     hidden_remainder_y
      - .offset:         198
        .size:           2
        .value_kind:     hidden_remainder_z
      - .offset:         216
        .size:           8
        .value_kind:     hidden_global_offset_x
      - .offset:         224
        .size:           8
        .value_kind:     hidden_global_offset_y
      - .offset:         232
        .size:           8
        .value_kind:     hidden_global_offset_z
      - .offset:         240
        .size:           2
        .value_kind:     hidden_grid_dims
      - .offset:         296
        .size:           4
        .value_kind:     hidden_dynamic_lds_size
    .group_segment_fixed_size: 0
    .kernarg_segment_align: 8
    .kernarg_segment_size: 432
    .language:       OpenCL C
    .language_version:
      - 2
      - 0
    .max_flat_workgroup_size: 512
    .name:           _Z3fwd4Args
    .private_segment_fixed_size: 0
    .sgpr_count:     106
    .sgpr_spill_count: 114
    .symbol:         _Z3fwd4Args.kd
    .uniform_work_group_size: 1
    .uses_dynamic_stack: false
    .vgpr_count:     256
    .vgpr_spill_count: 0
    .wavefront_size: 64
